# conv_mixer rows moved to WGs 128-255 (WGs 0-127 carry the long K-path UKV tile)
# speedup vs baseline: 1.0095x; 1.0095x over previous
; __device__ __forceinline__ int ltid() { int t = threadIdx.x; asm volatile("" : "+v"(t)); return t; }
; __device__ __forceinline__ int lbid() { int t = blockIdx.x; asm volatile("" : "+s"(t)); return t; }
; __device__ __forceinline__ void conv_mixer_rows(CArgs a, int layer, int G) {
;     const int lane = ltid() & 63, wave = ltid() >> 6;
;     const int gw = lbid() * NWAVES + wave, NGW = G * NWAVES;
;     const unsigned char* WSB = a->ws;
;     const bf16_t* U = (const bf16_t*)(a->ws + WS_U); bf16_t* Y = (bf16_t*)(a->ws + WS_Y);
;     const float* cw = a->conv_w + (size_t)layer * 3 * 512;
;     const int c0 = lane * 8;
;     float w[3][8];
; #pragma unroll
;     for (int k = 0; k < 3; ++k) { const f32x4 a0 = *(const f32x4*)(cw + k * 512 + c0), a1 = *(const f32x4*)(cw + k * 512 + c0 + 4);
;         w[k][0] = a0[0]; w[k][1] = a0[1]; w[k][2] = a0[2]; w[k][3] = a0[3]; w[k][4] = a1[0]; w[k][5] = a1[1]; w[k][6] = a1[2]; w[k][7] = a1[3]; }
;     auto load = [&](int row, u32x4 (&raw)[7]) {
;         const int s = row & (SEQ - 1);
; #pragma unroll
;         for (int k = 0; k < 3; ++k) {
;             const int sp = s + k - 1; const int rr = (sp >= 0 && sp < SEQ) ? row + k - 1 : row;
;             const bf16_t* ur = U + (size_t)rr * NU;
;             u32x4 h = *(const u32x4*)(ur + UCH + c0), c = *(const u32x4*)(ur + UCC + c0);
;             if (!(sp >= 0 && sp < SEQ)) { h = (u32x4){0u, 0u, 0u, 0u}; c = (u32x4){0u, 0u, 0u, 0u}; }
;             raw[2 * k] = h; raw[2 * k + 1] = c;
;         }
;         raw[6] = *(const u32x4*)(U + (size_t)row * NU + UCB + c0);
;     };
;     ...
;     for (int row = gw; row < T; row += 2 * NGW) {
;         const int row2 = row + NGW;
;         u32x4 ra[7], rb[7];
;         load(row, ra);
;         if (row2 < T) load(row2, rb);
.Lp4_conv_entry:
	s_load_dwordx2 s[60:61], s[6:7], 0xe8
	s_load_dwordx2 s[12:13], s[6:7], 0xa8
	v_readfirstlane_b32 s10, v244
	v_and_b32_e32 v2, 63, v244
	v_lshlrev_b32_e32 v6, 5, v2
	v_lshlrev_b32_e32 v2, 4, v2
	v_add_u32_e32 v3, 0x2000, v2
	v_add_u32_e32 v4, 0x1c00, v2
	v_add_u32_e32 v5, 0xc00, v2
	v_add_u32_e32 v2, 0x1800, v2
	v_readlane_b32 s17, v253, 0
	s_lshr_b32 s10, s10, 6
	s_lshl_b32 s16, s64, 3
	s_cmp_lg_u32 s64, 0x100
	s_cbranch_scc1 .Lcvm_map
	s_movk_i32 s16, 0x400
	s_sub_u32 s17, s17, 0x80
.Lcvm_map:
	s_lshl_b32 s17, s17, 3
	s_add_i32 s10, s10, s17
	s_mul_i32 s17, s8, 0x1800
	s_waitcnt lgkmcnt(0)
	s_and_b32 s61, s61, 0xffff
	s_add_u32 s12, s12, s17
	s_addc_u32 s13, s13, 0
	s_cmp_lt_u32 s10, 0x4000
	s_cbranch_scc0 .Lcvm_done
	global_load_dwordx4 v[8:11], v6, s[12:13]
	global_load_dwordx4 v[12:15], v6, s[12:13] offset:16
	global_load_dwordx4 v[16:19], v6, s[12:13] offset:2048
	global_load_dwordx4 v[20:23], v6, s[12:13] offset:2064
	s_add_u32 s12, s12, 0x1000
	s_addc_u32 s13, s13, 0
	global_load_dwordx4 v[24:27], v6, s[12:13]
	global_load_dwordx4 v[28:31], v6, s[12:13] offset:16
	s_and_b32 s21, s10, 0x7ff
	s_mul_i32 s19, s10, 0x2400
	s_add_u32 s19, s19, 0x3a00000
	s_sub_u32 s18, s19, 0x2400
	s_add_u32 s20, s19, 0x2400
	s_cmp_eq_u32 s21, 0
	s_cselect_b32 s18, s19, s18
	s_cmpk_eq_u32 s21, 0x7ff
	s_cselect_b32 s20, s19, s20
	buffer_load_dwordx4 v[32:35], v2, s[60:63], s18 offen
	buffer_load_dwordx4 v[36:39], v3, s[60:63], s18 offen
	buffer_load_dwordx4 v[40:43], v2, s[60:63], s19 offen
	buffer_load_dwordx4 v[44:47], v3, s[60:63], s19 offen
	buffer_load_dwordx4 v[48:51], v4, s[60:63], s19 offen
	buffer_load_dwordx4 v[52:55], v2, s[60:63], s20 offen
	buffer_load_dwordx4 v[56:59], v3, s[60:63], s20 offen
	s_mul_i32 s17, s16, 1
	s_add_i32 s17, s10, s17
	s_cmp_lt_u32 s17, 0x4000
	s_cselect_b32 s17, s17, s10
	s_and_b32 s21, s17, 0x7ff
	s_mul_i32 s19, s17, 0x2400
	s_add_u32 s19, s19, 0x3a00000
	s_sub_u32 s18, s19, 0x2400
	s_add_u32 s20, s19, 0x2400
	s_cmp_eq_u32 s21, 0
	s_cselect_b32 s18, s19, s18
	s_cmpk_eq_u32 s21, 0x7ff
	s_cselect_b32 s20, s19, s20
	buffer_load_dwordx4 v[60:63], v2, s[60:63], s18 offen
	buffer_load_dwordx4 v[64:67], v3, s[60:63], s18 offen
	buffer_load_dwordx4 v[68:71], v2, s[60:63], s19 offen
	buffer_load_dwordx4 v[72:75], v3, s[60:63], s19 offen
	buffer_load_dwordx4 v[76:79], v4, s[60:63], s19 offen
	buffer_load_dwordx4 v[80:83], v2, s[60:63], s20 offen
	buffer_load_dwordx4 v[84:87], v3, s[60:63], s20 offen
	s_mul_i32 s17, s16, 2
	s_add_i32 s17, s10, s17
	s_cmp_lt_u32 s17, 0x4000
	s_cselect_b32 s17, s17, s10
	s_and_b32 s21, s17, 0x7ff
	s_mul_i32 s19, s17, 0x2400
	s_add_u32 s19, s19, 0x3a00000
	s_sub_u32 s18, s19, 0x2400
	s_add_u32 s20, s19, 0x2400
	s_cmp_eq_u32 s21, 0
	s_cselect_b32 s18, s19, s18
	s_cmpk_eq_u32 s21, 0x7ff
	s_cselect_b32 s20, s19, s20
	buffer_load_dwordx4 v[88:91], v2, s[60:63], s18 offen
	buffer_load_dwordx4 v[92:95], v3, s[60:63], s18 offen
	buffer_load_dwordx4 v[96:99], v2, s[60:63], s19 offen
	buffer_load_dwordx4 v[100:103], v3, s[60:63], s19 offen
	buffer_load_dwordx4 v[104:107], v4, s[60:63], s19 offen
	buffer_load_dwordx4 v[108:111], v2, s[60:63], s20 offen
	buffer_load_dwordx4 v[112:115], v3, s[60:63], s20 offen
	s_waitcnt vmcnt(14)
	s_and_b32 s21, s10, 0x7ff
	s_cmp_lg_u32 s21, 0
	s_cbranch_scc1 .Lcvm_nz0_1
	v_mov_b32_e32 v32, 0
	v_mov_b32_e32 v33, 0
	v_mov_b32_e32 v34, 0
	v_mov_b32_e32 v35, 0
